# batched split-K partial loads in tail finalize (one wait instead of nch serial round trips)
# speedup vs baseline: 1.0056x; 1.0056x over previous
.LBB0_1445:
	s_lshl_b32 s0, s16, 2
	s_and_b32 s8, s0, 0x1e00
	s_ashr_i32 s0, s18, 4
	s_ashr_i32 s1, s0, 31
	s_lshl_b64 s[6:7], s[0:1], 13
	s_or_b32 s6, s6, s8
	v_mov_b32_e32 v6, 0
	s_waitcnt lgkmcnt(0)
	v_lshl_add_u64 v[8:9], v[4:5], 0, s[6:7]
	s_mov_b32 s1, s3
	v_mov_b32_e32 v7, v6
	s_cmp_gt_u32 s1, 22
	s_cbranch_scc1 .LBB0_1446
	s_mov_b64 s[6:7], 0x100000
	s_mov_b32 s99, s1
	global_load_dwordx2 v[70:71], v[8:9], off
	v_lshl_add_u64 v[8:9], v[8:9], 0, s[6:7]
	s_cmp_lt_u32 s99, 2
	s_cbranch_scc1 .Lmy_fin_issued
	global_load_dwordx2 v[72:73], v[8:9], off
	v_lshl_add_u64 v[8:9], v[8:9], 0, s[6:7]
	s_cmp_lt_u32 s99, 3
	s_cbranch_scc1 .Lmy_fin_issued
	global_load_dwordx2 v[74:75], v[8:9], off
	v_lshl_add_u64 v[8:9], v[8:9], 0, s[6:7]
	s_cmp_lt_u32 s99, 4
	s_cbranch_scc1 .Lmy_fin_issued
	global_load_dwordx2 v[76:77], v[8:9], off
	v_lshl_add_u64 v[8:9], v[8:9], 0, s[6:7]
	s_cmp_lt_u32 s99, 5
	s_cbranch_scc1 .Lmy_fin_issued
	global_load_dwordx2 v[78:79], v[8:9], off
	v_lshl_add_u64 v[8:9], v[8:9], 0, s[6:7]
	s_cmp_lt_u32 s99, 6
	s_cbranch_scc1 .Lmy_fin_issued
	global_load_dwordx2 v[80:81], v[8:9], off
	v_lshl_add_u64 v[8:9], v[8:9], 0, s[6:7]
	s_cmp_lt_u32 s99, 7
	s_cbranch_scc1 .Lmy_fin_issued
	global_load_dwordx2 v[82:83], v[8:9], off
	v_lshl_add_u64 v[8:9], v[8:9], 0, s[6:7]
	s_cmp_lt_u32 s99, 8
	s_cbranch_scc1 .Lmy_fin_issued
	global_load_dwordx2 v[84:85], v[8:9], off
	v_lshl_add_u64 v[8:9], v[8:9], 0, s[6:7]
	s_cmp_lt_u32 s99, 9
	s_cbranch_scc1 .Lmy_fin_issued
	global_load_dwordx2 v[86:87], v[8:9], off
	v_lshl_add_u64 v[8:9], v[8:9], 0, s[6:7]
	s_cmp_lt_u32 s99, 10
	s_cbranch_scc1 .Lmy_fin_issued
	global_load_dwordx2 v[88:89], v[8:9], off
	v_lshl_add_u64 v[8:9], v[8:9], 0, s[6:7]
	s_cmp_lt_u32 s99, 11
	s_cbranch_scc1 .Lmy_fin_issued
	global_load_dwordx2 v[90:91], v[8:9], off
	v_lshl_add_u64 v[8:9], v[8:9], 0, s[6:7]
	s_cmp_lt_u32 s99, 12
	s_cbranch_scc1 .Lmy_fin_issued
	global_load_dwordx2 v[92:93], v[8:9], off
	v_lshl_add_u64 v[8:9], v[8:9], 0, s[6:7]
	s_cmp_lt_u32 s99, 13
	s_cbranch_scc1 .Lmy_fin_issued
	global_load_dwordx2 v[94:95], v[8:9], off
	v_lshl_add_u64 v[8:9], v[8:9], 0, s[6:7]
	s_cmp_lt_u32 s99, 14
	s_cbranch_scc1 .Lmy_fin_issued
	global_load_dwordx2 v[96:97], v[8:9], off
	v_lshl_add_u64 v[8:9], v[8:9], 0, s[6:7]
	s_cmp_lt_u32 s99, 15
	s_cbranch_scc1 .Lmy_fin_issued
	global_load_dwordx2 v[98:99], v[8:9], off
	v_lshl_add_u64 v[8:9], v[8:9], 0, s[6:7]
	s_cmp_lt_u32 s99, 16
	s_cbranch_scc1 .Lmy_fin_issued
	global_load_dwordx2 v[100:101], v[8:9], off
	v_lshl_add_u64 v[8:9], v[8:9], 0, s[6:7]
	s_cmp_lt_u32 s99, 17
	s_cbranch_scc1 .Lmy_fin_issued
	global_load_dwordx2 v[102:103], v[8:9], off
	v_lshl_add_u64 v[8:9], v[8:9], 0, s[6:7]
	s_cmp_lt_u32 s99, 18
	s_cbranch_scc1 .Lmy_fin_issued
	global_load_dwordx2 v[104:105], v[8:9], off
	v_lshl_add_u64 v[8:9], v[8:9], 0, s[6:7]
	s_cmp_lt_u32 s99, 19
	s_cbranch_scc1 .Lmy_fin_issued
	global_load_dwordx2 v[106:107], v[8:9], off
	v_lshl_add_u64 v[8:9], v[8:9], 0, s[6:7]
	s_cmp_lt_u32 s99, 20
	s_cbranch_scc1 .Lmy_fin_issued
	global_load_dwordx2 v[108:109], v[8:9], off
	v_lshl_add_u64 v[8:9], v[8:9], 0, s[6:7]
	s_cmp_lt_u32 s99, 21
	s_cbranch_scc1 .Lmy_fin_issued
	global_load_dwordx2 v[110:111], v[8:9], off
	v_lshl_add_u64 v[8:9], v[8:9], 0, s[6:7]
	s_cmp_lt_u32 s99, 22
	s_cbranch_scc1 .Lmy_fin_issued
	global_load_dwordx2 v[112:113], v[8:9], off
.Lmy_fin_issued:
	s_add_i32 s6, s0, 0x4000
	s_lshl_b32 s1, s18, 7
	s_ashr_i32 s7, s6, 31
	s_and_b32 s1, s1, 0x780
	s_lshl_b64 s[8:9], s[6:7], 12
	s_add_u32 s8, s84, s8
	s_addc_u32 s9, s85, s9
	s_lshl_b32 s14, s1, 1
	s_add_u32 s8, s8, s14
	s_addc_u32 s9, s9, 0
	global_load_dword v3, v0, s[8:9]
	s_waitcnt vmcnt(0)
	v_pk_add_f32 v[6:7], v[6:7], v[70:71]
	s_cmp_lt_u32 s99, 2
	s_cbranch_scc1 .Lmy_fin_join
	v_pk_add_f32 v[6:7], v[6:7], v[72:73]
	s_cmp_lt_u32 s99, 3
	s_cbranch_scc1 .Lmy_fin_join
	v_pk_add_f32 v[6:7], v[6:7], v[74:75]
	s_cmp_lt_u32 s99, 4
	s_cbranch_scc1 .Lmy_fin_join
	v_pk_add_f32 v[6:7], v[6:7], v[76:77]
	s_cmp_lt_u32 s99, 5
	s_cbranch_scc1 .Lmy_fin_join
	v_pk_add_f32 v[6:7], v[6:7], v[78:79]
	s_cmp_lt_u32 s99, 6
	s_cbranch_scc1 .Lmy_fin_join
	v_pk_add_f32 v[6:7], v[6:7], v[80:81]
	s_cmp_lt_u32 s99, 7
	s_cbranch_scc1 .Lmy_fin_join
	v_pk_add_f32 v[6:7], v[6:7], v[82:83]
	s_cmp_lt_u32 s99, 8
	s_cbranch_scc1 .Lmy_fin_join
	v_pk_add_f32 v[6:7], v[6:7], v[84:85]
	s_cmp_lt_u32 s99, 9
	s_cbranch_scc1 .Lmy_fin_join
	v_pk_add_f32 v[6:7], v[6:7], v[86:87]
	s_cmp_lt_u32 s99, 10
	s_cbranch_scc1 .Lmy_fin_join
	v_pk_add_f32 v[6:7], v[6:7], v[88:89]
	s_cmp_lt_u32 s99, 11
	s_cbranch_scc1 .Lmy_fin_join
	v_pk_add_f32 v[6:7], v[6:7], v[90:91]
	s_cmp_lt_u32 s99, 12
	s_cbranch_scc1 .Lmy_fin_join
	v_pk_add_f32 v[6:7], v[6:7], v[92:93]
	s_cmp_lt_u32 s99, 13
	s_cbranch_scc1 .Lmy_fin_join
	v_pk_add_f32 v[6:7], v[6:7], v[94:95]
	s_cmp_lt_u32 s99, 14
	s_cbranch_scc1 .Lmy_fin_join
	v_pk_add_f32 v[6:7], v[6:7], v[96:97]
	s_cmp_lt_u32 s99, 15
	s_cbranch_scc1 .Lmy_fin_join
	v_pk_add_f32 v[6:7], v[6:7], v[98:99]
	s_cmp_lt_u32 s99, 16
	s_cbranch_scc1 .Lmy_fin_join
	v_pk_add_f32 v[6:7], v[6:7], v[100:101]
	s_cmp_lt_u32 s99, 17
	s_cbranch_scc1 .Lmy_fin_join
	v_pk_add_f32 v[6:7], v[6:7], v[102:103]
	s_cmp_lt_u32 s99, 18
	s_cbranch_scc1 .Lmy_fin_join
	v_pk_add_f32 v[6:7], v[6:7], v[104:105]
	s_cmp_lt_u32 s99, 19
	s_cbranch_scc1 .Lmy_fin_join
	v_pk_add_f32 v[6:7], v[6:7], v[106:107]
	s_cmp_lt_u32 s99, 20
	s_cbranch_scc1 .Lmy_fin_join
	v_pk_add_f32 v[6:7], v[6:7], v[108:109]
	s_cmp_lt_u32 s99, 21
	s_cbranch_scc1 .Lmy_fin_join
	v_pk_add_f32 v[6:7], v[6:7], v[110:111]
	s_cmp_lt_u32 s99, 22
	s_cbranch_scc1 .Lmy_fin_join
	v_pk_add_f32 v[6:7], v[6:7], v[112:113]
	s_branch .Lmy_fin_join

.Lmy_fin_join:
	s_mov_b64 s[14:15], -1
	s_and_b64 vcc, exec, s[10:11]
	s_waitcnt vmcnt(0)
	v_lshlrev_b32_e32 v8, 16, v3
	v_and_b32_e32 v9, 0xffff0000, v3
	v_pk_fma_f32 v[6:7], s[58:59], v[6:7], v[8:9]
	s_cbranch_vccz .LBB0_1454
	v_lshl_add_u64 v[8:9], s[8:9], 0, v[0:1]
	v_cvt_pk_bf16_f32 v3, v6, v7
	global_store_dword v[8:9], v3, off
	v_pk_mul_f32 v[8:9], v[6:7], v[6:7]
	s_nop 0
	v_add_f32_e32 v3, v8, v9
	v_and_b32_e32 v8, 64, v213
	v_add_u32_e32 v8, 64, v8
	v_xor_b32_e32 v9, 1, v213
	v_cmp_lt_i32_e32 vcc, v9, v8
	s_nop 1
	v_cndmask_b32_e32 v9, v213, v9, vcc
	v_lshlrev_b32_e32 v9, 2, v9
	ds_bpermute_b32 v9, v9, v3
	s_waitcnt lgkmcnt(0)
	v_add_f32_e32 v3, v3, v9
	v_xor_b32_e32 v9, 2, v213
	v_cmp_lt_i32_e32 vcc, v9, v8
	s_nop 1
	v_cndmask_b32_e32 v9, v213, v9, vcc
	v_lshlrev_b32_e32 v9, 2, v9
	ds_bpermute_b32 v9, v9, v3
	s_waitcnt lgkmcnt(0)
	v_add_f32_e32 v3, v3, v9
	v_xor_b32_e32 v9, 4, v213
	v_cmp_lt_i32_e32 vcc, v9, v8
	s_nop 1
	v_cndmask_b32_e32 v9, v213, v9, vcc
	v_lshlrev_b32_e32 v9, 2, v9
	ds_bpermute_b32 v9, v9, v3
	s_waitcnt lgkmcnt(0)
	v_add_f32_e32 v3, v3, v9
	v_xor_b32_e32 v9, 8, v213
	v_cmp_lt_i32_e32 vcc, v9, v8
	s_nop 1
	v_cndmask_b32_e32 v9, v213, v9, vcc
	v_lshlrev_b32_e32 v9, 2, v9
	ds_bpermute_b32 v9, v9, v3
	s_waitcnt lgkmcnt(0)
	v_add_f32_e32 v3, v3, v9
	v_xor_b32_e32 v9, 16, v213
	v_cmp_lt_i32_e32 vcc, v9, v8
	s_nop 1
	v_cndmask_b32_e32 v9, v213, v9, vcc
	v_lshlrev_b32_e32 v9, 2, v9
	ds_bpermute_b32 v9, v9, v3
	s_waitcnt lgkmcnt(0)
	v_add_f32_e32 v3, v3, v9
	v_xor_b32_e32 v9, 32, v213
	v_cmp_lt_i32_e32 vcc, v9, v8
	s_nop 1
	v_cndmask_b32_e32 v8, v213, v9, vcc
	v_lshlrev_b32_e32 v8, 2, v8
	ds_bpermute_b32 v8, v8, v3
	s_and_saveexec_b64 s[8:9], s[4:5]
	s_cbranch_execz .LBB0_1453
	s_mov_b64 s[14:15], exec
	s_waitcnt lgkmcnt(0)
	v_add_f32_e32 v8, v3, v8
	v_bfrev_b32_e32 v3, 1

	.amdhsa_kernel _Z8yoco_fwd4Args
		.amdhsa_group_segment_fixed_size 0
		.amdhsa_private_segment_fixed_size 0
		.amdhsa_kernarg_size 464
		.amdhsa_user_sgpr_count 2
		.amdhsa_user_sgpr_dispatch_ptr 0
		.amdhsa_user_sgpr_queue_ptr 0
		.amdhsa_user_sgpr_kernarg_segment_ptr 1
		.amdhsa_user_sgpr_dispatch_id 0
		.amdhsa_user_sgpr_kernarg_preload_length 0
		.amdhsa_user_sgpr_kernarg_preload_offset 0
		.amdhsa_user_sgpr_private_segment_size 0
		.amdhsa_uses_dynamic_stack 0
		.amdhsa_enable_private_segment 0
		.amdhsa_system_sgpr_workgroup_id_x 1
		.amdhsa_system_sgpr_workgroup_id_y 0
		.amdhsa_system_sgpr_workgroup_id_z 0
		.amdhsa_system_sgpr_workgroup_info 0
		.amdhsa_system_vgpr_workitem_id 2
		.amdhsa_next_free_vgpr 253
		.amdhsa_next_free_sgpr 100
		.amdhsa_accum_offset 256
		.amdhsa_reserve_vcc 1
		.amdhsa_float_round_mode_32 0
		.amdhsa_float_round_mode_16_64 0
		.amdhsa_float_denorm_mode_32 3
		.amdhsa_float_denorm_mode_16_64 3
		.amdhsa_dx10_clamp 1
		.amdhsa_ieee_mode 1
		.amdhsa_fp16_overflow 0
		.amdhsa_tg_split 0
		.amdhsa_exception_fp_ieee_invalid_op 0
		.amdhsa_exception_fp_denorm_src 0
		.amdhsa_exception_fp_ieee_div_zero 0
		.amdhsa_exception_fp_ieee_overflow 0
		.amdhsa_exception_fp_ieee_underflow 0
		.amdhsa_exception_fp_ieee_inexact 0
		.amdhsa_exception_int_div_zero 0
	.end_amdhsa_kernel

amdhsa.kernels:
  - .agpr_count:     0
    .args:
      - .offset:         0
        .size:           208
        .value_kind:     by_value
      - .offset:         208
        .size:           4
        .value_kind:     hidden_block_count_x
      - .offset:         212
        .size:           4
        .value_kind:     hidden_block_count_y
      - .offset:         216
        .size:           4
        .value_kind:     hidden_block_count_z
      - .offset:         220
        .size:           2
        .value_kind:     hidden_group_size_x
      - .offset:         222
        .size:           2
        .value_kind:     hidden_group_size_y
      - .offset:         224
        .size:           2
        .value_kind:     hidden_group_size_z
      - .offset:         226
        .size:           2
        .value_kind:     hidden_remainder_x
      - .offset:         228
        .size:           2
        .value_kind:     hidden_remainder_y
      - .offset:         230
        .size:           2
        .value_kind:     hidden_remainder_z
      - .offset:         248
        .size:           8
        .value_kind:     hidden_global_offset_x
      - .offset:         256
        .size:           8
        .value_kind:     hidden_global_offset_y
      - .offset:         264
        .size:           8
        .value_kind:     hidden_global_offset_z
      - .offset:         272
        .size:           2
        .value_kind:     hidden_grid_dims
      - .offset:         296
        .size:           8
        .value_kind:     hidden_multigrid_sync_arg
      - .offset:         328
        .size:           4
        .value_kind:     hidden_dynamic_lds_size
    .group_segment_fixed_size: 0
    .kernarg_segment_align: 8
    .kernarg_segment_size: 464
    .language:       OpenCL C
    .language_version:
      - 2
      - 0
    .max_flat_workgroup_size: 512
    .name:           _Z8yoco_fwd4Args
    .private_segment_fixed_size: 0
    .sgpr_count:     106
    .sgpr_spill_count: 294
    .symbol:         _Z8yoco_fwd4Args.kd
    .uniform_work_group_size: 1
    .uses_dynamic_stack: false
    .vgpr_count:     253
    .vgpr_spill_count: 0
    .wavefront_size: 64
